# conv/KV->Qup seam split into arrive + deferred wait before the first Q-up epilogue (WAR-only dependency), no L2 writeback in co-located mode
# baseline (speedup 1.0000x reference)
; __device__ __forceinline__ unsigned xb_ld(unsigned* p)              { return __hip_atomic_load(p, __ATOMIC_RELAXED, __HIP_MEMORY_SCOPE_AGENT); }
; __device__ __forceinline__ unsigned xb_add(unsigned* p, unsigned v) { return __hip_atomic_fetch_add(p, v, __ATOMIC_RELAXED, __HIP_MEMORY_SCOPE_AGENT); }
; #define XB_SPIN(cond, bar) do { unsigned _sp = 0; while (cond) { __builtin_amdgcn_s_sleep(1); \
;     if ((++_sp & 255u) == 0u) { if (xb_ld(&(bar)[XB_TMO])) break; if (_sp > XB_SPIN_CAP) { atomicAdd(&(bar)[XB_TMO], 1u); break; } } } } while (0)
; __device__ __forceinline__ void xcd_barrier(const XcdBarrier& b) {
;     asm volatile("s_waitcnt vmcnt(0)" ::: "memory");
;     __syncthreads();
;     if (threadIdx.x == 0) {
;         unsigned* bar = b.bar;
;         __builtin_amdgcn_s_waitcnt(0);
;         unsigned nloc = b.st[0], nx = b.st[1];
;         if (nloc == 0u) { xcd_barrier_complete(bar, b.x, nloc, nx); b.st[0] = nloc; b.st[1] = nx; }
;         const unsigned old = xb_add(&bar[XB_XSUB(b.x)], 1u);
;         const unsigned gen = old / nloc;
;         if (old + 1u == (gen + 1u) * nloc) {
;             __builtin_amdgcn_fence(__ATOMIC_RELEASE, "agent");
;             asm volatile("s_waitcnt vmcnt(0)" ::: "memory");
;             const unsigned og = xb_add(&bar[XB_TOP], 1u);
;             const unsigned tg = og / nx;
;             if (og + 1u == (tg + 1u) * nx) xb_add(&bar[XB_TOPGEN], 1u);
;             else XB_SPIN(xb_ld(&bar[XB_TOPGEN]) == tg, bar);
.LBB0_942:
	s_waitcnt vmcnt(0)
	s_waitcnt lgkmcnt(0)
	s_barrier
	s_mov_b64 s[0:1], exec
	v_readlane_b32 s2, v254, 5
	v_readlane_b32 s3, v254, 6
	s_and_b64 s[2:3], s[0:1], s[2:3]
	s_mov_b64 exec, s[2:3]
	s_cbranch_execz .LBB0_994
	s_cmp_lg_u32 s98, 0
	s_cbranch_scc1 .Lfb_orig_3
	v_readlane_b32 s4, v254, 4
	v_readlane_b32 s6, v254, 2
	v_readlane_b32 s7, v254, 3
	s_lshl_b32 s4, s4, 8
	s_add_u32 s4, s6, s4
	s_addc_u32 s5, s7, 0
	v_mov_b32_e32 v0, 0
	v_mov_b32_e32 v1, 1
	global_atomic_add v1, v0, v1, s[4:5] offset:1152 sc0
	s_waitcnt vmcnt(0)
	v_cmp_eq_u32_e32 vcc, 31, v1
	s_cbranch_vccz .LBB0_994
	v_mov_b32_e32 v0, 0x73900
	v_mov_b32_e32 v1, 1
	global_atomic_add v0, v1, s[90:91]
	s_branch .LBB0_994

;     __host__ __device__ bool next(int i, Unit& u) const {
;         const long L = (long)i * G + c; if (L >= nwg) return false;
;         int wgid = (int)L; { const int q = nwg / NXCD, r = nwg % NXCD, xcd = wgid % NXCD, off = wgid / NXCD; wgid = (xcd < r ? xcd * (q + 1) : r * (q + 1) + (xcd - r) * q) + off; }
;         const int nig = WGM * nN, gid = wgid / nig, fm = gid * WGM, gsz = (nM - fm) < WGM ? (nM - fm) : WGM;
;         u.pm = fm + ((wgid % nig) % gsz); u.pn = (wgid % nig) / gsz; return true;
; __global__ void __launch_bounds__(512, 2) fwd_kernel(Args a) {
;     ...
;         { pg8::Gemm g{(const bf16_t*)(P.ws + WS_QL), (const bf16_t*)(P.ws + WS_WUQ), T, 1536, QLORA}; pg8::StaticOrder S; S.init(T, 1536, G, bx);
;           EpiQUp E{P.ws};
;           pg8::gemm_phase<EpiQUp, pg8::StaticOrder, true, true>(lds, g, S, E); }
.LBB0_994:
	s_or_b64 exec, exec, s[0:1]
	s_cmp_eq_u32 s98, 0
	s_cselect_b32 s100, 1, 0
	s_cmpk_lt_i32 s80, 0x300
	v_readfirstlane_b32 s11, v200
	s_movk_i32 s0, 0x180
	s_cselect_b64 s[2:3], -1, 0
	s_cmpk_gt_i32 s80, 0x2ff
	s_waitcnt lgkmcnt(0)
	s_barrier
	s_cbranch_scc1 .LBB0_996
	s_ashr_i32 s1, s80, 31
	s_lshr_b32 s1, s1, 29
	s_add_i32 s1, s80, s1
	s_ashr_i32 s4, s1, 3
	s_and_b32 s1, s1, -8
	s_sub_i32 s1, s80, s1
	s_cmp_lt_i32 s1, 0
	s_movk_i32 s5, 0x61
	s_cselect_b32 s5, s5, 0x60
	s_mul_i32 s1, s1, s5
	s_add_i32 s1, s1, s4
	s_mul_hi_i32 s4, s1, 0x2aaaaaab
	s_lshr_b32 s5, s4, 31
	s_ashr_i32 s4, s4, 3
	s_add_i32 s4, s4, s5
	s_lshl_b32 s5, s4, 3
	s_mul_i32 s4, s4, 48
	s_sub_i32 s1, s1, s4
	s_bfe_i32 s4, s1, 0x80000
	s_bfe_u32 s4, s4, 0x3000c
	s_add_i32 s4, s1, s4
	s_bfe_i32 s6, s4, 0x80000
	s_and_b32 s4, s4, 0xf8
	s_sub_i32 s1, s1, s4
	s_sext_i32_i16 s6, s6
	s_sext_i32_i8 s1, s1
	s_add_i32 s10, s5, s1
	s_ashr_i32 s28, s6, 3

; #define PG8_BAR __builtin_amdgcn_s_barrier()
; template <class Epi, class Sched, bool ALIGN_EPI = false, bool SP2 = false>
; __device__ __forceinline__ void gemm_phase(PG8_LAS unsigned char* lds, const Gemm g, const Sched& S, const Epi& E) {
;     ...
;         if constexpr (ALIGN_EPI) { if (wr == 0) PG8_BAR; }
;         if constexpr (!Epi::AFTER_DRAIN) { E(acc, cur, wr, wc, fr, fq); S.done(cur); }
;     __device__ __forceinline__ void operator()(const AccT& acc, const Unit& u, int wr, int wc, int fr_, int fq_) const {
;     ...
;         const int pn = u.pn;
;         bf16_t* const QI = (bf16_t*)(ws + WS_QIMG); const float* const ssq_q = (const float*)(ws + WS_SSQ); const float* const rope = (const float*)(ws + WS_ROPE);
;         float ssv[2][4];
; #pragma unroll
;         for (int ai = 0; ai < 2; ++ai)
; #pragma unroll
;             for (int m = 0; m < 4; ++m) ssv[ai][m] = ssq_q[(size_t)ROW_OF(ai, m)];
.LBB0_1013:
	s_cmp_eq_u32 s100, 0
	s_cbranch_scc1 .Lq_skip
	s_mov_b64 s[4:5], exec
	v_readlane_b32 s100, v254, 5
	v_readlane_b32 s101, v254, 6
	s_and_b64 s[100:101], s[4:5], s[100:101]
	s_mov_b64 exec, s[100:101]
	s_cbranch_execz .Lq_join
	v_mov_b32_e32 v184, 0x73900
	v_mov_b32_e32 v186, 0
.Lq_spin:
	global_load_dword v185, v184, s[90:91] sc1
	v_add_u32_e32 v186, 1, v186
	s_waitcnt vmcnt(0)
	v_cmp_le_u32_e32 vcc, 8, v185
	s_cbranch_vccnz .Lq_join
	v_cmp_gt_u32_e32 vcc, 0x8000, v186
	s_cbranch_vccnz .Lq_spin
.Lq_join:
	s_mov_b64 exec, s[4:5]
	s_mov_b32 s100, 0
	s_barrier

; __global__ void __launch_bounds__(512, 2) fwd_kernel(Args a) {
	.amdhsa_kernel _Z10fwd_kernel4Args
		.amdhsa_group_segment_fixed_size 0
		.amdhsa_private_segment_fixed_size 0
		.amdhsa_kernarg_size 408
		.amdhsa_user_sgpr_count 2
		.amdhsa_user_sgpr_dispatch_ptr 0
		.amdhsa_user_sgpr_queue_ptr 0
		.amdhsa_user_sgpr_kernarg_segment_ptr 1
		.amdhsa_user_sgpr_dispatch_id 0
		.amdhsa_user_sgpr_kernarg_preload_length 0
		.amdhsa_user_sgpr_kernarg_preload_offset 0
		.amdhsa_user_sgpr_private_segment_size 0
		.amdhsa_uses_dynamic_stack 0
		.amdhsa_enable_private_segment 0
		.amdhsa_system_sgpr_workgroup_id_x 1
		.amdhsa_system_sgpr_workgroup_id_y 0
		.amdhsa_system_sgpr_workgroup_id_z 0
		.amdhsa_system_sgpr_workgroup_info 0
		.amdhsa_system_vgpr_workitem_id 2
		.amdhsa_next_free_vgpr 256
		.amdhsa_next_free_sgpr 102
		.amdhsa_accum_offset 256
		.amdhsa_reserve_vcc 1
		.amdhsa_float_round_mode_32 0
		.amdhsa_float_round_mode_16_64 0
		.amdhsa_float_denorm_mode_32 3
		.amdhsa_float_denorm_mode_16_64 3
		.amdhsa_dx10_clamp 1
		.amdhsa_ieee_mode 1
		.amdhsa_fp16_overflow 0
		.amdhsa_tg_split 0
		.amdhsa_exception_fp_ieee_invalid_op 0
		.amdhsa_exception_fp_denorm_src 0
		.amdhsa_exception_fp_ieee_div_zero 0
		.amdhsa_exception_fp_ieee_overflow 0
		.amdhsa_exception_fp_ieee_underflow 0
		.amdhsa_exception_fp_ieee_inexact 0
		.amdhsa_exception_int_div_zero 0
	.end_amdhsa_kernel

; __global__ void __launch_bounds__(512, 2) fwd_kernel(Args a) {
.Lfunc_end0:
	.size	_Z10fwd_kernel4Args, .Lfunc_end0-_Z10fwd_kernel4Args
	.set _Z10fwd_kernel4Args.num_vgpr, 256
	.set _Z10fwd_kernel4Args.num_agpr, 0
	.set _Z10fwd_kernel4Args.numbered_sgpr, 102
	.set _Z10fwd_kernel4Args.num_named_barrier, 0
	.set _Z10fwd_kernel4Args.private_seg_size, 0
	.set _Z10fwd_kernel4Args.uses_vcc, 1
	.set _Z10fwd_kernel4Args.uses_flat_scratch, 0
	.set _Z10fwd_kernel4Args.has_dyn_sized_stack, 0
	.set _Z10fwd_kernel4Args.has_recursion, 0
	.set _Z10fwd_kernel4Args.has_indirect_call, 0

; __global__ void __launch_bounds__(512, 2) fwd_kernel(Args a) {
amdhsa.kernels:
  - .agpr_count:     0
    .args:
      - .offset:         0
        .size:           152
        .value_kind:     by_value
      - .offset:         152
        .size:           4
        .value_kind:     hidden_block_count_x
      - .offset:         156
        .size:           4
        .value_kind:     hidden_block_count_y
      - .offset:         160
        .size:           4
        .value_kind:     hidden_block_count_z
      - .offset:         164
        .size:           2
        .value_kind:     hidden_group_size_x
      - .offset:         166
        .size:           2
        .value_kind:     hidden_group_size_y
      - .offset:         168
        .size:           2
        .value_kind:     hidden_group_size_z
      - .offset:         170
        .size:           2
        .value_kind:     hidden_remainder_x
      - .offset:         172
        .size:           2
        .value_kind:     hidden_remainder_y
      - .offset:         174
        .size:           2
        .value_kind:     hidden_remainder_z
      - .offset:         192
        .size:           8
        .value_kind:     hidden_global_offset_x
      - .offset:         200
        .size:           8
        .value_kind:     hidden_global_offset_y
      - .offset:         208
        .size:           8
        .value_kind:     hidden_global_offset_z
      - .offset:         216
        .size:           2
        .value_kind:     hidden_grid_dims
      - .offset:         240
        .size:           8
        .value_kind:     hidden_multigrid_sync_arg
      - .offset:         272
        .size:           4
        .value_kind:     hidden_dynamic_lds_size
    .group_segment_fixed_size: 0
    .kernarg_segment_align: 8
    .kernarg_segment_size: 408
    .language:       OpenCL C
    .language_version:
      - 2
      - 0
    .max_flat_workgroup_size: 512
    .name:           _Z10fwd_kernel4Args
    .private_segment_fixed_size: 0
    .sgpr_count:     108
    .sgpr_spill_count: 83
    .symbol:         _Z10fwd_kernel4Args.kd
    .uniform_work_group_size: 1
    .uses_dynamic_stack: false
    .vgpr_count:     256
    .vgpr_spill_count: 0
    .wavefront_size: 64
